# v022 + last G4 tile: phase 2 with all sum-of-squares loads up front and output stores paced (short sleep between row blocks); first tile of WGs 0-7 keeps the original phase 2
# speedup vs baseline: 1.0135x; 1.0013x over previous
;     __device__ __forceinline__ void operator()(f32x4 (&acc)[2][2][4][2], const pg8::Unit& u, int wr, int wc, int fr, int fq) const {
;     ...
;         f32x4 gg[2][2];
; #pragma unroll
;         for (int bj = 0; bj < 2; ++bj)
; #pragma unroll
;             for (int n = 0; n < 2; ++n) gg[bj][n] = *(const f32x4*)(fng + col0 + bj * 128 + n * 16);
; #pragma unroll
;         for (int ai = 0; ai < 2; ++ai)
; #pragma unroll
;             for (int m = 0; m < 4; ++m) {
;                 const int row = row0 + ai * 128 + m * 16;
;                 const f32x4 pa = *(const f32x4*)(ss + (size_t)row * 32 + 8 * fq), pb = *(const f32x4*)(ss + (size_t)row * 32 + 8 * fq + 4);
;                 float sq = ((pa[0] + pa[1]) + (pa[2] + pa[3])) + ((pb[0] + pb[1]) + (pb[2] + pb[3]));
;                 sq += __shfl_xor(sq, 16); sq += __shfl_xor(sq, 32);
;                 const float rinv = __builtin_amdgcn_rsqf(sq * (1.0f / DM) + 1e-6f);
.LBB0_904:
	s_or_b64 exec, exec, s[36:37]
	s_barrier
	s_and_b64 vcc, exec, s[34:35]
	s_cbranch_vccnz .Lp2_orig
	s_waitcnt lgkmcnt(0)
	v_lshl_add_u64 v[130:131], v[148:149], 0, v[130:131]
	v_lshl_add_u64 v[166:167], v[148:149], 0, v[166:167]
	v_lshl_add_u64 v[168:169], v[148:149], 0, v[168:169]
	v_lshl_add_u64 v[170:171], v[148:149], 0, v[170:171]
	v_lshl_add_u64 v[172:173], v[148:149], 0, v[172:173]
	v_lshl_add_u64 v[174:175], v[148:149], 0, v[174:175]
	v_lshl_add_u64 v[176:177], v[148:149], 0, v[176:177]
	v_lshl_add_u64 v[178:179], v[148:149], 0, v[178:179]
	v_readlane_b32 s64, v234, 3
	v_readlane_b32 s74, v234, 13
	v_readlane_b32 s75, v234, 14
	global_load_dwordx4 v[196:199], v[130:131], off
	global_load_dwordx4 v[200:203], v[130:131], off offset:16
	global_load_dwordx4 v[204:207], v[166:167], off
	global_load_dwordx4 v[208:211], v[166:167], off offset:16
	global_load_dwordx4 v[212:215], v[168:169], off
	global_load_dwordx4 v[216:219], v[168:169], off offset:16
	global_load_dwordx4 v[220:223], v[170:171], off
	global_load_dwordx4 v[224:227], v[170:171], off offset:16
	global_load_dwordx4 v[228:231], v[172:173], off
	global_load_dwordx4 v[236:239], v[172:173], off offset:16
	global_load_dwordx4 v[240:243], v[174:175], off
	global_load_dwordx4 v[244:247], v[174:175], off offset:16
	global_load_dwordx4 v[248:251], v[176:177], off
	global_load_dwordx4 v[188:191], v[176:177], off offset:16
	global_load_dwordx4 v[152:155], v[178:179], off
	global_load_dwordx4 v[156:159], v[178:179], off offset:16
	v_lshl_add_u64 v[128:129], v[128:129], 2, s[74:75]
	global_load_dwordx4 v[140:143], v[128:129], off
	global_load_dwordx4 v[136:139], v[128:129], off offset:64
	global_load_dwordx4 v[132:135], v[128:129], off offset:512
	s_nop 0
	global_load_dwordx4 v[128:131], v[128:129], off offset:576
	v_readlane_b32 s65, v234, 4
	v_readlane_b32 s66, v234, 5
	v_readlane_b32 s67, v234, 6
	v_readlane_b32 s68, v234, 7
	v_readlane_b32 s69, v234, 8
	v_readlane_b32 s70, v234, 9
	v_readlane_b32 s71, v234, 10
	v_readlane_b32 s72, v234, 11
	v_readlane_b32 s73, v234, 12
	v_readlane_b32 s76, v234, 15
	v_readlane_b32 s77, v234, 16
	v_readlane_b32 s78, v234, 17
	v_readlane_b32 s79, v234, 18
	s_waitcnt vmcnt(18)
	v_add_f32_e32 v196, v196, v197
	v_add_f32_e32 v198, v198, v199
	v_add_f32_e32 v200, v200, v201
	v_add_f32_e32 v202, v202, v203
	v_add_f32_e32 v196, v196, v198
	v_add_f32_e32 v200, v200, v202
	v_add_f32_e32 v196, v196, v200
	ds_bpermute_b32 v197, v185, v196
	s_waitcnt vmcnt(16)
	v_add_f32_e32 v204, v204, v205
	v_add_f32_e32 v206, v206, v207
	v_add_f32_e32 v208, v208, v209
	v_add_f32_e32 v210, v210, v211
	v_add_f32_e32 v204, v204, v206
	v_add_f32_e32 v208, v208, v210
	v_add_f32_e32 v204, v204, v208
	ds_bpermute_b32 v205, v185, v204
	s_waitcnt vmcnt(14)
	v_add_f32_e32 v212, v212, v213
	v_add_f32_e32 v214, v214, v215
	v_add_f32_e32 v216, v216, v217
	v_add_f32_e32 v218, v218, v219
	v_add_f32_e32 v212, v212, v214
	v_add_f32_e32 v216, v216, v218
	v_add_f32_e32 v212, v212, v216
	ds_bpermute_b32 v213, v185, v212
	s_waitcnt vmcnt(12)
	v_add_f32_e32 v220, v220, v221
	v_add_f32_e32 v222, v222, v223
	v_add_f32_e32 v224, v224, v225
	v_add_f32_e32 v226, v226, v227
	v_add_f32_e32 v220, v220, v222
	v_add_f32_e32 v224, v224, v226
	v_add_f32_e32 v220, v220, v224
	ds_bpermute_b32 v221, v185, v220
	s_waitcnt vmcnt(10)
	v_add_f32_e32 v228, v228, v229
	v_add_f32_e32 v230, v230, v231
	v_add_f32_e32 v236, v236, v237
	v_add_f32_e32 v238, v238, v239
	v_add_f32_e32 v228, v228, v230
	v_add_f32_e32 v236, v236, v238
	v_add_f32_e32 v228, v228, v236
	ds_bpermute_b32 v229, v185, v228
	s_waitcnt vmcnt(8)
	v_add_f32_e32 v240, v240, v241
	v_add_f32_e32 v242, v242, v243
	v_add_f32_e32 v244, v244, v245
	v_add_f32_e32 v246, v246, v247
	v_add_f32_e32 v240, v240, v242
	v_add_f32_e32 v244, v244, v246
	v_add_f32_e32 v240, v240, v244
	ds_bpermute_b32 v241, v185, v240
	s_waitcnt vmcnt(6)
	v_add_f32_e32 v248, v248, v249
	v_add_f32_e32 v250, v250, v251
	v_add_f32_e32 v188, v188, v189
	v_add_f32_e32 v190, v190, v191
	v_add_f32_e32 v248, v248, v250
	v_add_f32_e32 v188, v188, v190
	v_add_f32_e32 v248, v248, v188
	ds_bpermute_b32 v249, v185, v248
	s_waitcnt vmcnt(4)
	v_add_f32_e32 v152, v152, v153
	v_add_f32_e32 v154, v154, v155
	v_add_f32_e32 v156, v156, v157
	v_add_f32_e32 v158, v158, v159
	v_add_f32_e32 v152, v152, v154
	v_add_f32_e32 v156, v156, v158
	v_add_f32_e32 v152, v152, v156
	ds_bpermute_b32 v153, v185, v152
	s_waitcnt lgkmcnt(7)
	v_add_f32_e32 v196, v196, v197
	ds_bpermute_b32 v197, v186, v196
	s_waitcnt lgkmcnt(7)
	v_add_f32_e32 v204, v204, v205
	ds_bpermute_b32 v205, v186, v204
	s_waitcnt lgkmcnt(7)
	v_add_f32_e32 v212, v212, v213
	ds_bpermute_b32 v213, v186, v212
	s_waitcnt lgkmcnt(7)
	v_add_f32_e32 v220, v220, v221
	ds_bpermute_b32 v221, v186, v220
	s_waitcnt lgkmcnt(7)
	v_add_f32_e32 v228, v228, v229
	ds_bpermute_b32 v229, v186, v228
	s_waitcnt lgkmcnt(7)
	v_add_f32_e32 v240, v240, v241
	ds_bpermute_b32 v241, v186, v240
	s_waitcnt lgkmcnt(7)
	v_add_f32_e32 v248, v248, v249
	ds_bpermute_b32 v249, v186, v248
	s_waitcnt lgkmcnt(7)
	v_add_f32_e32 v152, v152, v153
	ds_bpermute_b32 v153, v186, v152
	s_waitcnt lgkmcnt(7)
	v_add_f32_e32 v196, v196, v197
	v_fmamk_f32 v196, v196, 0x3a000000, v184
	v_rsq_f32_e32 v196, v196
	s_waitcnt lgkmcnt(6)
	v_add_f32_e32 v204, v204, v205
	v_fmamk_f32 v204, v204, 0x3a000000, v184
	v_rsq_f32_e32 v204, v204
	s_waitcnt lgkmcnt(5)
	v_add_f32_e32 v212, v212, v213
	v_fmamk_f32 v212, v212, 0x3a000000, v184
	v_rsq_f32_e32 v212, v212
	s_waitcnt lgkmcnt(4)
	v_add_f32_e32 v220, v220, v221
	v_fmamk_f32 v220, v220, 0x3a000000, v184
	v_rsq_f32_e32 v220, v220
	s_waitcnt lgkmcnt(3)
;     __device__ __forceinline__ void operator()(f32x4 (&acc)[2][2][4][2], const pg8::Unit& u, int wr, int wc, int fr, int fq) const {
;     ...
;                 const float rinv = __builtin_amdgcn_rsqf(sq * (1.0f / DM) + 1e-6f);
;                 float* orow = oy + (size_t)row * DM + col0;
; #pragma unroll
;                 for (int bj = 0; bj < 2; ++bj)
; #pragma unroll
;                     for (int n = 0; n < 2; ++n) __builtin_nontemporal_store(acc[ai][bj][m][n] * rinv * gg[bj][n], (f32x4*)(orow + bj * 128 + n * 16));
	v_add_f32_e32 v228, v228, v229
	v_fmamk_f32 v228, v228, 0x3a000000, v184
	v_rsq_f32_e32 v228, v228
	s_waitcnt lgkmcnt(2)
	v_add_f32_e32 v240, v240, v241
	v_fmamk_f32 v240, v240, 0x3a000000, v184
	v_rsq_f32_e32 v240, v240
	s_waitcnt lgkmcnt(1)
	v_add_f32_e32 v248, v248, v249
	v_fmamk_f32 v248, v248, 0x3a000000, v184
	v_rsq_f32_e32 v248, v248
	s_waitcnt lgkmcnt(0)
	v_add_f32_e32 v152, v152, v153
	v_fmamk_f32 v152, v152, 0x3a000000, v184
	v_rsq_f32_e32 v152, v152
	s_nop 0
	s_waitcnt vmcnt(0)
	v_pk_mul_f32 v[124:125], v[124:125], v[196:197] op_sel_hi:[1,0]
	v_pk_mul_f32 v[126:127], v[126:127], v[196:197] op_sel_hi:[1,0]
	v_pk_mul_f32 v[120:121], v[120:121], v[196:197] op_sel_hi:[1,0]
	v_pk_mul_f32 v[122:123], v[122:123], v[196:197] op_sel_hi:[1,0]
	v_pk_mul_f32 v[92:93], v[92:93], v[196:197] op_sel_hi:[1,0]
	v_pk_mul_f32 v[94:95], v[94:95], v[196:197] op_sel_hi:[1,0]
	v_pk_mul_f32 v[88:89], v[88:89], v[196:197] op_sel_hi:[1,0]
	v_pk_mul_f32 v[90:91], v[90:91], v[196:197] op_sel_hi:[1,0]
	v_pk_mul_f32 v[124:125], v[140:141], v[124:125]
	v_pk_mul_f32 v[126:127], v[142:143], v[126:127]
	v_pk_mul_f32 v[120:121], v[136:137], v[120:121]
	v_pk_mul_f32 v[122:123], v[138:139], v[122:123]
	v_pk_mul_f32 v[92:93], v[132:133], v[92:93]
	v_pk_mul_f32 v[94:95], v[134:135], v[94:95]
	v_pk_mul_f32 v[88:89], v[128:129], v[88:89]
	v_pk_mul_f32 v[90:91], v[130:131], v[90:91]
	global_store_dwordx4 v[150:151], v[124:127], off nt
	global_store_dwordx4 v[150:151], v[120:123], off offset:64 nt
	global_store_dwordx4 v[150:151], v[92:95], off offset:512 nt
	global_store_dwordx4 v[150:151], v[88:91], off offset:576 nt
	s_sleep 12
	s_mov_b64 s[88:89], 0x20000
	v_lshl_add_u64 v[162:163], v[150:151], 0, s[88:89]
	v_pk_mul_f32 v[116:117], v[116:117], v[204:205] op_sel_hi:[1,0]
	v_pk_mul_f32 v[118:119], v[118:119], v[204:205] op_sel_hi:[1,0]
	v_pk_mul_f32 v[112:113], v[112:113], v[204:205] op_sel_hi:[1,0]
	v_pk_mul_f32 v[114:115], v[114:115], v[204:205] op_sel_hi:[1,0]
	v_pk_mul_f32 v[84:85], v[84:85], v[204:205] op_sel_hi:[1,0]
	v_pk_mul_f32 v[86:87], v[86:87], v[204:205] op_sel_hi:[1,0]
	v_pk_mul_f32 v[80:81], v[80:81], v[204:205] op_sel_hi:[1,0]
	v_pk_mul_f32 v[82:83], v[82:83], v[204:205] op_sel_hi:[1,0]
	v_pk_mul_f32 v[116:117], v[140:141], v[116:117]
	v_pk_mul_f32 v[118:119], v[142:143], v[118:119]
	v_pk_mul_f32 v[112:113], v[136:137], v[112:113]
	v_pk_mul_f32 v[114:115], v[138:139], v[114:115]
	v_pk_mul_f32 v[84:85], v[132:133], v[84:85]
	v_pk_mul_f32 v[86:87], v[134:135], v[86:87]
	v_pk_mul_f32 v[80:81], v[128:129], v[80:81]
	v_pk_mul_f32 v[82:83], v[130:131], v[82:83]
	global_store_dwordx4 v[162:163], v[116:119], off nt
	global_store_dwordx4 v[162:163], v[112:115], off offset:64 nt
	global_store_dwordx4 v[162:163], v[84:87], off offset:512 nt
	global_store_dwordx4 v[162:163], v[80:83], off offset:576 nt
	s_sleep 12
	s_mov_b64 s[88:89], 0x40000
	v_lshl_add_u64 v[164:165], v[150:151], 0, s[88:89]
	v_pk_mul_f32 v[108:109], v[108:109], v[212:213] op_sel_hi:[1,0]
	v_pk_mul_f32 v[110:111], v[110:111], v[212:213] op_sel_hi:[1,0]
	v_pk_mul_f32 v[104:105], v[104:105], v[212:213] op_sel_hi:[1,0]
	v_pk_mul_f32 v[106:107], v[106:107], v[212:213] op_sel_hi:[1,0]
	v_pk_mul_f32 v[76:77], v[76:77], v[212:213] op_sel_hi:[1,0]
	v_pk_mul_f32 v[78:79], v[78:79], v[212:213] op_sel_hi:[1,0]
	v_pk_mul_f32 v[72:73], v[72:73], v[212:213] op_sel_hi:[1,0]
	v_pk_mul_f32 v[74:75], v[74:75], v[212:213] op_sel_hi:[1,0]
	v_pk_mul_f32 v[108:109], v[140:141], v[108:109]
	v_pk_mul_f32 v[110:111], v[142:143], v[110:111]
	v_pk_mul_f32 v[104:105], v[136:137], v[104:105]
	v_pk_mul_f32 v[106:107], v[138:139], v[106:107]
	v_pk_mul_f32 v[76:77], v[132:133], v[76:77]
	v_pk_mul_f32 v[78:79], v[134:135], v[78:79]
	v_pk_mul_f32 v[72:73], v[128:129], v[72:73]
	v_pk_mul_f32 v[74:75], v[130:131], v[74:75]
	global_store_dwordx4 v[164:165], v[108:111], off nt
	global_store_dwordx4 v[164:165], v[104:107], off offset:64 nt
	global_store_dwordx4 v[164:165], v[76:79], off offset:512 nt
	global_store_dwordx4 v[164:165], v[72:75], off offset:576 nt
	s_sleep 12
	s_mov_b64 s[88:89], 0x60000
	v_lshl_add_u64 v[160:161], v[150:151], 0, s[88:89]
	v_pk_mul_f32 v[100:101], v[100:101], v[220:221] op_sel_hi:[1,0]
	v_pk_mul_f32 v[102:103], v[102:103], v[220:221] op_sel_hi:[1,0]
	v_pk_mul_f32 v[96:97], v[96:97], v[220:221] op_sel_hi:[1,0]
	v_pk_mul_f32 v[98:99], v[98:99], v[220:221] op_sel_hi:[1,0]
	v_pk_mul_f32 v[68:69], v[68:69], v[220:221] op_sel_hi:[1,0]
	v_pk_mul_f32 v[70:71], v[70:71], v[220:221] op_sel_hi:[1,0]
	v_pk_mul_f32 v[64:65], v[64:65], v[220:221] op_sel_hi:[1,0]
	v_pk_mul_f32 v[66:67], v[66:67], v[220:221] op_sel_hi:[1,0]
	v_pk_mul_f32 v[100:101], v[140:141], v[100:101]
	v_pk_mul_f32 v[102:103], v[142:143], v[102:103]
	v_pk_mul_f32 v[96:97], v[136:137], v[96:97]
	v_pk_mul_f32 v[98:99], v[138:139], v[98:99]
	v_pk_mul_f32 v[68:69], v[132:133], v[68:69]
	v_pk_mul_f32 v[70:71], v[134:135], v[70:71]
	v_pk_mul_f32 v[64:65], v[128:129], v[64:65]
	v_pk_mul_f32 v[66:67], v[130:131], v[66:67]
	global_store_dwordx4 v[160:161], v[100:103], off nt
	global_store_dwordx4 v[160:161], v[96:99], off offset:64 nt
	global_store_dwordx4 v[160:161], v[68:71], off offset:512 nt
	global_store_dwordx4 v[160:161], v[64:67], off offset:576 nt
	s_sleep 12
	s_mov_b64 s[88:89], 0x100000
	v_lshl_add_u64 v[162:163], v[150:151], 0, s[88:89]
	v_pk_mul_f32 v[60:61], v[60:61], v[228:229] op_sel_hi:[1,0]
	v_pk_mul_f32 v[62:63], v[62:63], v[228:229] op_sel_hi:[1,0]
	v_pk_mul_f32 v[56:57], v[56:57], v[228:229] op_sel_hi:[1,0]
	v_pk_mul_f32 v[58:59], v[58:59], v[228:229] op_sel_hi:[1,0]
	v_pk_mul_f32 v[28:29], v[28:29], v[228:229] op_sel_hi:[1,0]
;     __device__ __forceinline__ void operator()(f32x4 (&acc)[2][2][4][2], const pg8::Unit& u, int wr, int wc, int fr, int fq) const {
;     ...
;                 float* orow = oy + (size_t)row * DM + col0;
; #pragma unroll
;                 for (int bj = 0; bj < 2; ++bj)
; #pragma unroll
;                     for (int n = 0; n < 2; ++n) __builtin_nontemporal_store(acc[ai][bj][m][n] * rinv * gg[bj][n], (f32x4*)(orow + bj * 128 + n * 16));
	v_pk_mul_f32 v[30:31], v[30:31], v[228:229] op_sel_hi:[1,0]
	v_pk_mul_f32 v[24:25], v[24:25], v[228:229] op_sel_hi:[1,0]
	v_pk_mul_f32 v[26:27], v[26:27], v[228:229] op_sel_hi:[1,0]
	v_pk_mul_f32 v[60:61], v[140:141], v[60:61]
	v_pk_mul_f32 v[62:63], v[142:143], v[62:63]
	v_pk_mul_f32 v[56:57], v[136:137], v[56:57]
	v_pk_mul_f32 v[58:59], v[138:139], v[58:59]
	v_pk_mul_f32 v[28:29], v[132:133], v[28:29]
	v_pk_mul_f32 v[30:31], v[134:135], v[30:31]
	v_pk_mul_f32 v[24:25], v[128:129], v[24:25]
	v_pk_mul_f32 v[26:27], v[130:131], v[26:27]
	global_store_dwordx4 v[162:163], v[60:63], off nt
	global_store_dwordx4 v[162:163], v[56:59], off offset:64 nt
	global_store_dwordx4 v[162:163], v[28:31], off offset:512 nt
	global_store_dwordx4 v[162:163], v[24:27], off offset:576 nt
	s_sleep 12
	s_mov_b64 s[88:89], 0x120000
	v_lshl_add_u64 v[164:165], v[150:151], 0, s[88:89]
	v_pk_mul_f32 v[52:53], v[52:53], v[240:241] op_sel_hi:[1,0]
	v_pk_mul_f32 v[54:55], v[54:55], v[240:241] op_sel_hi:[1,0]
	v_pk_mul_f32 v[48:49], v[48:49], v[240:241] op_sel_hi:[1,0]
	v_pk_mul_f32 v[50:51], v[50:51], v[240:241] op_sel_hi:[1,0]
	v_pk_mul_f32 v[20:21], v[20:21], v[240:241] op_sel_hi:[1,0]
	v_pk_mul_f32 v[22:23], v[22:23], v[240:241] op_sel_hi:[1,0]
	v_pk_mul_f32 v[16:17], v[16:17], v[240:241] op_sel_hi:[1,0]
	v_pk_mul_f32 v[18:19], v[18:19], v[240:241] op_sel_hi:[1,0]
	v_pk_mul_f32 v[52:53], v[140:141], v[52:53]
	v_pk_mul_f32 v[54:55], v[142:143], v[54:55]
	v_pk_mul_f32 v[48:49], v[136:137], v[48:49]
	v_pk_mul_f32 v[50:51], v[138:139], v[50:51]
	v_pk_mul_f32 v[20:21], v[132:133], v[20:21]
	v_pk_mul_f32 v[22:23], v[134:135], v[22:23]
	v_pk_mul_f32 v[16:17], v[128:129], v[16:17]
	v_pk_mul_f32 v[18:19], v[130:131], v[18:19]
	global_store_dwordx4 v[164:165], v[52:55], off nt
	global_store_dwordx4 v[164:165], v[48:51], off offset:64 nt
	global_store_dwordx4 v[164:165], v[20:23], off offset:512 nt
	global_store_dwordx4 v[164:165], v[16:19], off offset:576 nt
	s_sleep 12
	s_mov_b64 s[88:89], 0x140000
	v_lshl_add_u64 v[160:161], v[150:151], 0, s[88:89]
	v_pk_mul_f32 v[44:45], v[44:45], v[248:249] op_sel_hi:[1,0]
	v_pk_mul_f32 v[46:47], v[46:47], v[248:249] op_sel_hi:[1,0]
	v_pk_mul_f32 v[40:41], v[40:41], v[248:249] op_sel_hi:[1,0]
	v_pk_mul_f32 v[42:43], v[42:43], v[248:249] op_sel_hi:[1,0]
	v_pk_mul_f32 v[12:13], v[12:13], v[248:249] op_sel_hi:[1,0]
	v_pk_mul_f32 v[14:15], v[14:15], v[248:249] op_sel_hi:[1,0]
	v_pk_mul_f32 v[8:9], v[8:9], v[248:249] op_sel_hi:[1,0]
	v_pk_mul_f32 v[10:11], v[10:11], v[248:249] op_sel_hi:[1,0]
	v_pk_mul_f32 v[44:45], v[140:141], v[44:45]
	v_pk_mul_f32 v[46:47], v[142:143], v[46:47]
	v_pk_mul_f32 v[40:41], v[136:137], v[40:41]
	v_pk_mul_f32 v[42:43], v[138:139], v[42:43]
	v_pk_mul_f32 v[12:13], v[132:133], v[12:13]
	v_pk_mul_f32 v[14:15], v[134:135], v[14:15]
	v_pk_mul_f32 v[8:9], v[128:129], v[8:9]
	v_pk_mul_f32 v[10:11], v[130:131], v[10:11]
	global_store_dwordx4 v[160:161], v[44:47], off nt
	global_store_dwordx4 v[160:161], v[40:43], off offset:64 nt
	global_store_dwordx4 v[160:161], v[12:15], off offset:512 nt
	global_store_dwordx4 v[160:161], v[8:11], off offset:576 nt
	s_sleep 12
	s_mov_b64 s[88:89], 0x160000
	v_lshl_add_u64 v[162:163], v[150:151], 0, s[88:89]
	v_pk_mul_f32 v[36:37], v[36:37], v[152:153] op_sel_hi:[1,0]
	v_pk_mul_f32 v[38:39], v[38:39], v[152:153] op_sel_hi:[1,0]
	v_pk_mul_f32 v[32:33], v[32:33], v[152:153] op_sel_hi:[1,0]
	v_pk_mul_f32 v[34:35], v[34:35], v[152:153] op_sel_hi:[1,0]
	v_pk_mul_f32 v[4:5], v[4:5], v[152:153] op_sel_hi:[1,0]
	v_pk_mul_f32 v[6:7], v[6:7], v[152:153] op_sel_hi:[1,0]
	v_pk_mul_f32 v[0:1], v[0:1], v[152:153] op_sel_hi:[1,0]
	v_pk_mul_f32 v[2:3], v[2:3], v[152:153] op_sel_hi:[1,0]
	v_pk_mul_f32 v[36:37], v[140:141], v[36:37]
	v_pk_mul_f32 v[38:39], v[142:143], v[38:39]
	v_pk_mul_f32 v[32:33], v[136:137], v[32:33]
	v_pk_mul_f32 v[34:35], v[138:139], v[34:35]
	v_pk_mul_f32 v[4:5], v[132:133], v[4:5]
	v_pk_mul_f32 v[6:7], v[134:135], v[6:7]
	v_pk_mul_f32 v[0:1], v[128:129], v[0:1]
	v_pk_mul_f32 v[2:3], v[130:131], v[2:3]
	global_store_dwordx4 v[162:163], v[36:39], off nt
	global_store_dwordx4 v[162:163], v[32:35], off offset:64 nt
	global_store_dwordx4 v[162:163], v[4:7], off offset:512 nt
	global_store_dwordx4 v[162:163], v[0:3], off offset:576 nt
	s_sleep 12
	s_andn2_b64 vcc, exec, s[34:35]
	s_branch .Lp2_done
;     __device__ __forceinline__ void operator()(f32x4 (&acc)[2][2][4][2], const pg8::Unit& u, int wr, int wc, int fr, int fq) const {
;     ...
;         for (int ai = 0; ai < 2; ++ai)
; #pragma unroll
;             for (int m = 0; m < 4; ++m) {
;                 const int row = row0 + ai * 128 + m * 16;
;                 const f32x4 pa = *(const f32x4*)(ss + (size_t)row * 32 + 8 * fq), pb = *(const f32x4*)(ss + (size_t)row * 32 + 8 * fq + 4);
;                 float sq = ((pa[0] + pa[1]) + (pa[2] + pa[3])) + ((pb[0] + pb[1]) + (pb[2] + pb[3]));
;                 sq += __shfl_xor(sq, 16); sq += __shfl_xor(sq, 32);
;                 const float rinv = __builtin_amdgcn_rsqf(sq * (1.0f / DM) + 1e-6f);
;                 float* orow = oy + (size_t)row * DM + col0;
; #pragma unroll
;                 for (int bj = 0; bj < 2; ++bj)
; #pragma unroll
;                     for (int n = 0; n < 2; ++n) __builtin_nontemporal_store(acc[ai][bj][m][n] * rinv * gg[bj][n], (f32x4*)(orow + bj * 128 + n * 16));
.Lp2_orig:
	v_lshl_add_u64 v[130:131], v[148:149], 0, v[130:131]
	global_load_dwordx4 v[188:191], v[130:131], off
	global_load_dwordx4 v[196:199], v[130:131], off offset:16
	v_readlane_b32 s64, v234, 3
	v_readlane_b32 s74, v234, 13
	v_readlane_b32 s75, v234, 14
	v_lshl_add_u64 v[166:167], v[148:149], 0, v[166:167]
	v_lshl_add_u64 v[170:171], v[148:149], 0, v[170:171]
	v_lshl_add_u64 v[128:129], v[128:129], 2, s[74:75]
	global_load_dwordx4 v[140:143], v[128:129], off
	global_load_dwordx4 v[136:139], v[128:129], off offset:64
	s_waitcnt lgkmcnt(0)
	global_load_dwordx4 v[132:135], v[128:129], off offset:512
	s_nop 0
	global_load_dwordx4 v[128:131], v[128:129], off offset:576
	v_lshl_add_u64 v[174:175], v[148:149], 0, v[174:175]
	s_andn2_b64 vcc, exec, s[34:35]
	v_readlane_b32 s65, v234, 4
	v_readlane_b32 s66, v234, 5
	v_readlane_b32 s67, v234, 6
	v_readlane_b32 s68, v234, 7
	v_readlane_b32 s69, v234, 8
	v_readlane_b32 s70, v234, 9
	v_readlane_b32 s71, v234, 10
	v_readlane_b32 s72, v234, 11
	v_readlane_b32 s73, v234, 12
	v_readlane_b32 s76, v234, 15
	v_readlane_b32 s77, v234, 16
	v_readlane_b32 s78, v234, 17
	v_readlane_b32 s79, v234, 18
	s_waitcnt vmcnt(5)
	v_mov_b32_e32 v192, v188
	s_waitcnt vmcnt(4)
	v_mov_b32_e32 v193, v196
	v_mov_b32_e32 v196, v189
	v_mov_b32_e32 v188, v190
	v_mov_b32_e32 v189, v198
	v_mov_b32_e32 v198, v191
	v_pk_add_f32 v[190:191], v[192:193], v[196:197]
	v_pk_add_f32 v[188:189], v[188:189], v[198:199]
	s_nop 0
	v_pk_add_f32 v[188:189], v[190:191], v[188:189]
	s_nop 0
	v_add_f32_e32 v187, v188, v189
	ds_bpermute_b32 v188, v185, v187
	s_waitcnt lgkmcnt(0)
	v_add_f32_e32 v187, v187, v188
	ds_bpermute_b32 v188, v186, v187
	s_waitcnt lgkmcnt(0)
	v_add_f32_e32 v187, v187, v188
	v_fmamk_f32 v187, v187, 0x3a000000, v184
	v_rsq_f32_e32 v188, v187
	s_nop 0
	v_pk_mul_f32 v[192:193], v[124:125], v[188:189] op_sel_hi:[1,0]
	v_pk_mul_f32 v[190:191], v[126:127], v[188:189] op_sel_hi:[1,0]
	v_pk_mul_f32 v[196:197], v[120:121], v[188:189] op_sel_hi:[1,0]
	v_pk_mul_f32 v[198:199], v[122:123], v[188:189] op_sel_hi:[1,0]
	v_pk_mul_f32 v[200:201], v[92:93], v[188:189] op_sel_hi:[1,0]
	v_pk_mul_f32 v[202:203], v[94:95], v[188:189] op_sel_hi:[1,0]
	v_pk_mul_f32 v[204:205], v[88:89], v[188:189] op_sel_hi:[1,0]
	v_pk_mul_f32 v[206:207], v[90:91], v[188:189] op_sel_hi:[1,0]
	s_waitcnt vmcnt(3)
	v_pk_mul_f32 v[190:191], v[142:143], v[190:191]
	v_pk_mul_f32 v[188:189], v[140:141], v[192:193]
	s_waitcnt vmcnt(2)
	v_pk_mul_f32 v[198:199], v[138:139], v[198:199]
	v_pk_mul_f32 v[196:197], v[136:137], v[196:197]
	s_waitcnt vmcnt(1)
	v_pk_mul_f32 v[202:203], v[134:135], v[202:203]
	v_pk_mul_f32 v[200:201], v[132:133], v[200:201]
	s_waitcnt vmcnt(0)
	v_pk_mul_f32 v[206:207], v[130:131], v[206:207]
	v_pk_mul_f32 v[204:205], v[128:129], v[204:205]
	global_store_dwordx4 v[150:151], v[188:191], off nt
	global_store_dwordx4 v[150:151], v[196:199], off offset:64 nt
	global_store_dwordx4 v[150:151], v[200:203], off offset:512 nt
	global_store_dwordx4 v[150:151], v[204:207], off offset:576 nt
	global_load_dwordx4 v[188:191], v[166:167], off
	s_nop 0
	global_load_dwordx4 v[196:199], v[166:167], off offset:16
	v_lshl_add_u64 v[192:193], v[148:149], 0, v[168:169]
	s_waitcnt vmcnt(1)
	v_mov_b32_e32 v150, v188
	s_waitcnt vmcnt(0)
	v_mov_b32_e32 v151, v196
	v_mov_b32_e32 v196, v189
	v_mov_b32_e32 v166, v190
	v_mov_b32_e32 v167, v198
	v_mov_b32_e32 v198, v191
	v_pk_add_f32 v[150:151], v[150:151], v[196:197]
	v_pk_add_f32 v[166:167], v[166:167], v[198:199]
	s_nop 0
	v_pk_add_f32 v[150:151], v[150:151], v[166:167]
	s_nop 0
	v_add_f32_e32 v150, v150, v151
	ds_bpermute_b32 v151, v185, v150
	s_waitcnt lgkmcnt(0)
	v_add_f32_e32 v150, v150, v151
	ds_bpermute_b32 v151, v186, v150
	s_waitcnt lgkmcnt(0)
	v_add_f32_e32 v150, v150, v151
	v_fmamk_f32 v150, v150, 0x3a000000, v184
	v_rsq_f32_e32 v150, v150
	s_nop 0
	v_pk_mul_f32 v[166:167], v[116:117], v[150:151] op_sel_hi:[1,0]
	v_pk_mul_f32 v[168:169], v[118:119], v[150:151] op_sel_hi:[1,0]
	v_pk_mul_f32 v[188:189], v[112:113], v[150:151] op_sel_hi:[1,0]
	v_pk_mul_f32 v[190:191], v[114:115], v[150:151] op_sel_hi:[1,0]
	v_pk_mul_f32 v[196:197], v[84:85], v[150:151] op_sel_hi:[1,0]
	v_pk_mul_f32 v[198:199], v[86:87], v[150:151] op_sel_hi:[1,0]
	v_pk_mul_f32 v[200:201], v[80:81], v[150:151] op_sel_hi:[1,0]
	v_pk_mul_f32 v[150:151], v[82:83], v[150:151] op_sel_hi:[1,0]
	v_pk_mul_f32 v[168:169], v[142:143], v[168:169]
	v_pk_mul_f32 v[166:167], v[140:141], v[166:167]
	v_pk_mul_f32 v[190:191], v[138:139], v[190:191]
	v_pk_mul_f32 v[188:189], v[136:137], v[188:189]
	v_pk_mul_f32 v[198:199], v[134:135], v[198:199]
	v_pk_mul_f32 v[196:197], v[132:133], v[196:197]
	v_pk_mul_f32 v[202:203], v[130:131], v[150:151]
	v_pk_mul_f32 v[200:201], v[128:129], v[200:201]
	global_store_dwordx4 v[152:153], v[166:169], off nt
	global_store_dwordx4 v[152:153], v[188:191], off offset:64 nt
	global_store_dwordx4 v[152:153], v[196:199], off offset:512 nt
	global_store_dwordx4 v[152:153], v[200:203], off offset:576 nt
	global_load_dwordx4 v[150:153], v[192:193], off
	s_nop 0
	global_load_dwordx4 v[166:169], v[192:193], off offset:16
	s_waitcnt vmcnt(1)
	v_mov_b32_e32 v188, v150
	s_waitcnt vmcnt(0)
	v_mov_b32_e32 v189, v166
	v_mov_b32_e32 v166, v151
	v_mov_b32_e32 v150, v152
	v_mov_b32_e32 v151, v168
	v_mov_b32_e32 v168, v153
	v_pk_add_f32 v[152:153], v[188:189], v[166:167]
	v_pk_add_f32 v[150:151], v[150:151], v[168:169]
	s_nop 0
	v_pk_add_f32 v[150:151], v[152:153], v[150:151]
	s_nop 0
	v_add_f32_e32 v150, v150, v151
	ds_bpermute_b32 v151, v185, v150
	s_waitcnt lgkmcnt(0)
	v_add_f32_e32 v150, v150, v151
	ds_bpermute_b32 v151, v186, v150
	s_waitcnt lgkmcnt(0)
;     __device__ __forceinline__ void operator()(f32x4 (&acc)[2][2][4][2], const pg8::Unit& u, int wr, int wc, int fr, int fq) const {
;     ...
;         for (int ai = 0; ai < 2; ++ai)
; #pragma unroll
;             for (int m = 0; m < 4; ++m) {
;                 const int row = row0 + ai * 128 + m * 16;
;                 const f32x4 pa = *(const f32x4*)(ss + (size_t)row * 32 + 8 * fq), pb = *(const f32x4*)(ss + (size_t)row * 32 + 8 * fq + 4);
;                 float sq = ((pa[0] + pa[1]) + (pa[2] + pa[3])) + ((pb[0] + pb[1]) + (pb[2] + pb[3]));
;                 sq += __shfl_xor(sq, 16); sq += __shfl_xor(sq, 32);
;                 const float rinv = __builtin_amdgcn_rsqf(sq * (1.0f / DM) + 1e-6f);
;                 float* orow = oy + (size_t)row * DM + col0;
; #pragma unroll
;                 for (int bj = 0; bj < 2; ++bj)
; #pragma unroll
;                     for (int n = 0; n < 2; ++n) __builtin_nontemporal_store(acc[ai][bj][m][n] * rinv * gg[bj][n], (f32x4*)(orow + bj * 128 + n * 16));
	v_add_f32_e32 v150, v150, v151
	v_fmamk_f32 v150, v150, 0x3a000000, v184
	v_rsq_f32_e32 v150, v150
	s_nop 0
	v_pk_mul_f32 v[166:167], v[108:109], v[150:151] op_sel_hi:[1,0]
	v_pk_mul_f32 v[152:153], v[110:111], v[150:151] op_sel_hi:[1,0]
	v_pk_mul_f32 v[188:189], v[104:105], v[150:151] op_sel_hi:[1,0]
	v_pk_mul_f32 v[168:169], v[106:107], v[150:151] op_sel_hi:[1,0]
	v_pk_mul_f32 v[192:193], v[76:77], v[150:151] op_sel_hi:[1,0]
	v_pk_mul_f32 v[190:191], v[78:79], v[150:151] op_sel_hi:[1,0]
	v_pk_mul_f32 v[196:197], v[72:73], v[150:151] op_sel_hi:[1,0]
	v_pk_mul_f32 v[198:199], v[74:75], v[150:151] op_sel_hi:[1,0]
	v_pk_mul_f32 v[152:153], v[142:143], v[152:153]
	v_pk_mul_f32 v[150:151], v[140:141], v[166:167]
	v_pk_mul_f32 v[168:169], v[138:139], v[168:169]
	v_pk_mul_f32 v[166:167], v[136:137], v[188:189]
	v_pk_mul_f32 v[190:191], v[134:135], v[190:191]
	v_pk_mul_f32 v[188:189], v[132:133], v[192:193]
	v_pk_mul_f32 v[198:199], v[130:131], v[198:199]
	v_pk_mul_f32 v[196:197], v[128:129], v[196:197]
	global_store_dwordx4 v[154:155], v[150:153], off nt
	global_store_dwordx4 v[154:155], v[166:169], off offset:64 nt
	global_store_dwordx4 v[154:155], v[188:191], off offset:512 nt
	global_store_dwordx4 v[154:155], v[196:199], off offset:576 nt
	global_load_dwordx4 v[150:153], v[170:171], off
	s_nop 0
	global_load_dwordx4 v[166:169], v[170:171], off offset:16
	s_waitcnt vmcnt(1)
	v_mov_b32_e32 v154, v150
	s_waitcnt vmcnt(0)
	v_mov_b32_e32 v155, v166
	v_mov_b32_e32 v166, v151
	v_mov_b32_e32 v150, v152
	v_mov_b32_e32 v151, v168
	v_mov_b32_e32 v168, v153
	v_pk_add_f32 v[152:153], v[154:155], v[166:167]
	v_pk_add_f32 v[150:151], v[150:151], v[168:169]
	v_lshl_add_u64 v[154:155], v[148:149], 0, v[172:173]
	v_pk_add_f32 v[150:151], v[152:153], v[150:151]
	s_nop 0
	v_add_f32_e32 v150, v150, v151
	ds_bpermute_b32 v151, v185, v150
	s_waitcnt lgkmcnt(0)
	v_add_f32_e32 v150, v150, v151
	ds_bpermute_b32 v151, v186, v150
	s_waitcnt lgkmcnt(0)
	v_add_f32_e32 v150, v150, v151
	v_fmamk_f32 v150, v150, 0x3a000000, v184
	v_rsq_f32_e32 v150, v150
	s_nop 0
	v_pk_mul_f32 v[166:167], v[100:101], v[150:151] op_sel_hi:[1,0]
	v_pk_mul_f32 v[152:153], v[102:103], v[150:151] op_sel_hi:[1,0]
	v_pk_mul_f32 v[170:171], v[96:97], v[150:151] op_sel_hi:[1,0]
	v_pk_mul_f32 v[168:169], v[98:99], v[150:151] op_sel_hi:[1,0]
	v_pk_mul_f32 v[188:189], v[68:69], v[150:151] op_sel_hi:[1,0]
	v_pk_mul_f32 v[172:173], v[70:71], v[150:151] op_sel_hi:[1,0]
	v_pk_mul_f32 v[192:193], v[64:65], v[150:151] op_sel_hi:[1,0]
	v_pk_mul_f32 v[190:191], v[66:67], v[150:151] op_sel_hi:[1,0]
	v_pk_mul_f32 v[152:153], v[142:143], v[152:153]
	v_pk_mul_f32 v[150:151], v[140:141], v[166:167]
	v_pk_mul_f32 v[168:169], v[138:139], v[168:169]
	v_pk_mul_f32 v[166:167], v[136:137], v[170:171]
	v_pk_mul_f32 v[172:173], v[134:135], v[172:173]
	v_pk_mul_f32 v[170:171], v[132:133], v[188:189]
	v_pk_mul_f32 v[190:191], v[130:131], v[190:191]
	v_pk_mul_f32 v[188:189], v[128:129], v[192:193]
	global_store_dwordx4 v[156:157], v[150:153], off nt
	global_store_dwordx4 v[156:157], v[166:169], off offset:64 nt
	global_store_dwordx4 v[156:157], v[170:173], off offset:512 nt
	global_store_dwordx4 v[156:157], v[188:191], off offset:576 nt
	global_load_dwordx4 v[150:153], v[154:155], off
	s_nop 0
	global_load_dwordx4 v[154:157], v[154:155], off offset:16
	s_waitcnt vmcnt(1)
	v_mov_b32_e32 v166, v150
	s_waitcnt vmcnt(0)
	v_mov_b32_e32 v167, v154
	v_mov_b32_e32 v154, v151
	v_mov_b32_e32 v150, v152
	v_mov_b32_e32 v151, v156
	v_mov_b32_e32 v156, v153
	v_pk_add_f32 v[152:153], v[166:167], v[154:155]
	v_pk_add_f32 v[150:151], v[150:151], v[156:157]
	s_nop 0
	v_pk_add_f32 v[150:151], v[152:153], v[150:151]
	s_nop 0
	v_add_f32_e32 v150, v150, v151
	ds_bpermute_b32 v151, v185, v150
	s_waitcnt lgkmcnt(0)
	v_add_f32_e32 v150, v150, v151
	ds_bpermute_b32 v151, v186, v150
	s_waitcnt lgkmcnt(0)
	v_add_f32_e32 v150, v150, v151
	v_fmamk_f32 v150, v150, 0x3a000000, v184
	v_rsq_f32_e32 v150, v150
	s_nop 0
	v_pk_mul_f32 v[154:155], v[60:61], v[150:151] op_sel_hi:[1,0]
	v_pk_mul_f32 v[152:153], v[62:63], v[150:151] op_sel_hi:[1,0]
	v_pk_mul_f32 v[166:167], v[56:57], v[150:151] op_sel_hi:[1,0]
	v_pk_mul_f32 v[156:157], v[58:59], v[150:151] op_sel_hi:[1,0]
	v_pk_mul_f32 v[170:171], v[28:29], v[150:151] op_sel_hi:[1,0]
	v_pk_mul_f32 v[168:169], v[30:31], v[150:151] op_sel_hi:[1,0]
	v_pk_mul_f32 v[188:189], v[24:25], v[150:151] op_sel_hi:[1,0]
	v_pk_mul_f32 v[172:173], v[26:27], v[150:151] op_sel_hi:[1,0]
	v_pk_mul_f32 v[152:153], v[142:143], v[152:153]
	v_pk_mul_f32 v[150:151], v[140:141], v[154:155]
	v_pk_mul_f32 v[156:157], v[138:139], v[156:157]
	v_pk_mul_f32 v[154:155], v[136:137], v[166:167]
	v_pk_mul_f32 v[168:169], v[134:135], v[168:169]
	v_pk_mul_f32 v[166:167], v[132:133], v[170:171]
	v_pk_mul_f32 v[172:173], v[130:131], v[172:173]
	v_pk_mul_f32 v[170:171], v[128:129], v[188:189]
	global_store_dwordx4 v[158:159], v[150:153], off nt
	global_store_dwordx4 v[158:159], v[154:157], off offset:64 nt
	global_store_dwordx4 v[158:159], v[166:169], off offset:512 nt
	global_store_dwordx4 v[158:159], v[170:173], off offset:576 nt
	global_load_dwordx4 v[150:153], v[174:175], off
	s_nop 0
	global_load_dwordx4 v[154:157], v[174:175], off offset:16
	s_waitcnt vmcnt(1)
	v_mov_b32_e32 v158, v150
	s_waitcnt vmcnt(0)
	v_mov_b32_e32 v159, v154
	v_mov_b32_e32 v154, v151
	v_mov_b32_e32 v150, v152
	v_mov_b32_e32 v151, v156
	v_mov_b32_e32 v156, v153
	v_pk_add_f32 v[152:153], v[158:159], v[154:155]
	v_pk_add_f32 v[150:151], v[150:151], v[156:157]
	v_lshl_add_u64 v[158:159], v[148:149], 0, v[176:177]
	v_pk_add_f32 v[150:151], v[152:153], v[150:151]
	s_nop 0
	v_add_f32_e32 v150, v150, v151
	ds_bpermute_b32 v151, v185, v150
	s_waitcnt lgkmcnt(0)
;     __device__ __forceinline__ void operator()(f32x4 (&acc)[2][2][4][2], const pg8::Unit& u, int wr, int wc, int fr, int fq) const {
;     ...
;         for (int ai = 0; ai < 2; ++ai)
; #pragma unroll
;             for (int m = 0; m < 4; ++m) {
;                 const int row = row0 + ai * 128 + m * 16;
;                 const f32x4 pa = *(const f32x4*)(ss + (size_t)row * 32 + 8 * fq), pb = *(const f32x4*)(ss + (size_t)row * 32 + 8 * fq + 4);
;                 float sq = ((pa[0] + pa[1]) + (pa[2] + pa[3])) + ((pb[0] + pb[1]) + (pb[2] + pb[3]));
;                 sq += __shfl_xor(sq, 16); sq += __shfl_xor(sq, 32);
;                 const float rinv = __builtin_amdgcn_rsqf(sq * (1.0f / DM) + 1e-6f);
;                 float* orow = oy + (size_t)row * DM + col0;
; #pragma unroll
;                 for (int bj = 0; bj < 2; ++bj)
; #pragma unroll
;                     for (int n = 0; n < 2; ++n) __builtin_nontemporal_store(acc[ai][bj][m][n] * rinv * gg[bj][n], (f32x4*)(orow + bj * 128 + n * 16));
	v_add_f32_e32 v150, v150, v151
	ds_bpermute_b32 v151, v186, v150
	s_waitcnt lgkmcnt(0)
	v_add_f32_e32 v150, v150, v151
	v_fmamk_f32 v150, v150, 0x3a000000, v184
	v_rsq_f32_e32 v150, v150
	s_nop 0
	v_pk_mul_f32 v[154:155], v[52:53], v[150:151] op_sel_hi:[1,0]
	v_pk_mul_f32 v[152:153], v[54:55], v[150:151] op_sel_hi:[1,0]
	v_pk_mul_f32 v[166:167], v[48:49], v[150:151] op_sel_hi:[1,0]
	v_pk_mul_f32 v[156:157], v[50:51], v[150:151] op_sel_hi:[1,0]
	v_pk_mul_f32 v[170:171], v[20:21], v[150:151] op_sel_hi:[1,0]
	v_pk_mul_f32 v[168:169], v[22:23], v[150:151] op_sel_hi:[1,0]
	v_pk_mul_f32 v[174:175], v[16:17], v[150:151] op_sel_hi:[1,0]
	v_pk_mul_f32 v[172:173], v[18:19], v[150:151] op_sel_hi:[1,0]
	v_pk_mul_f32 v[152:153], v[142:143], v[152:153]
	v_pk_mul_f32 v[150:151], v[140:141], v[154:155]
	v_pk_mul_f32 v[156:157], v[138:139], v[156:157]
	v_pk_mul_f32 v[154:155], v[136:137], v[166:167]
	v_pk_mul_f32 v[168:169], v[134:135], v[168:169]
	v_pk_mul_f32 v[166:167], v[132:133], v[170:171]
	v_pk_mul_f32 v[172:173], v[130:131], v[172:173]
	v_pk_mul_f32 v[170:171], v[128:129], v[174:175]
	global_store_dwordx4 v[160:161], v[150:153], off nt
	global_store_dwordx4 v[160:161], v[154:157], off offset:64 nt
	global_store_dwordx4 v[160:161], v[166:169], off offset:512 nt
	global_store_dwordx4 v[160:161], v[170:173], off offset:576 nt
	global_load_dwordx4 v[150:153], v[158:159], off
	s_nop 0
	global_load_dwordx4 v[154:157], v[158:159], off offset:16
	v_lshl_add_u64 v[170:171], v[148:149], 0, v[178:179]
	s_waitcnt vmcnt(1)
	v_mov_b32_e32 v158, v150
	s_waitcnt vmcnt(0)
	v_mov_b32_e32 v159, v154
	v_mov_b32_e32 v154, v151
	v_mov_b32_e32 v150, v152
	v_mov_b32_e32 v151, v156
	v_mov_b32_e32 v156, v153
	v_pk_add_f32 v[152:153], v[158:159], v[154:155]
	v_pk_add_f32 v[150:151], v[150:151], v[156:157]
	s_nop 0
	v_pk_add_f32 v[150:151], v[152:153], v[150:151]
	s_nop 0
	v_add_f32_e32 v150, v150, v151
	ds_bpermute_b32 v151, v185, v150
	s_waitcnt lgkmcnt(0)
	v_add_f32_e32 v150, v150, v151
	ds_bpermute_b32 v151, v186, v150
	s_waitcnt lgkmcnt(0)
	v_add_f32_e32 v150, v150, v151
	v_fmamk_f32 v150, v150, 0x3a000000, v184
	v_rsq_f32_e32 v150, v150
	s_nop 0
	v_pk_mul_f32 v[154:155], v[44:45], v[150:151] op_sel_hi:[1,0]
	v_pk_mul_f32 v[152:153], v[46:47], v[150:151] op_sel_hi:[1,0]
	v_pk_mul_f32 v[158:159], v[40:41], v[150:151] op_sel_hi:[1,0]
	v_pk_mul_f32 v[156:157], v[42:43], v[150:151] op_sel_hi:[1,0]
	v_pk_mul_f32 v[166:167], v[12:13], v[150:151] op_sel_hi:[1,0]
	v_pk_mul_f32 v[160:161], v[14:15], v[150:151] op_sel_hi:[1,0]
	v_pk_mul_f32 v[172:173], v[8:9], v[150:151] op_sel_hi:[1,0]
	v_pk_mul_f32 v[168:169], v[10:11], v[150:151] op_sel_hi:[1,0]
	v_pk_mul_f32 v[152:153], v[142:143], v[152:153]
	v_pk_mul_f32 v[150:151], v[140:141], v[154:155]
	v_pk_mul_f32 v[156:157], v[138:139], v[156:157]
	v_pk_mul_f32 v[154:155], v[136:137], v[158:159]
	v_pk_mul_f32 v[160:161], v[134:135], v[160:161]
	v_pk_mul_f32 v[158:159], v[132:133], v[166:167]
	v_pk_mul_f32 v[168:169], v[130:131], v[168:169]
	v_pk_mul_f32 v[166:167], v[128:129], v[172:173]
	global_store_dwordx4 v[162:163], v[150:153], off nt
	global_store_dwordx4 v[162:163], v[154:157], off offset:64 nt
	global_store_dwordx4 v[162:163], v[158:161], off offset:512 nt
	global_store_dwordx4 v[162:163], v[166:169], off offset:576 nt
	global_load_dwordx4 v[150:153], v[170:171], off
	s_nop 0
	global_load_dwordx4 v[154:157], v[170:171], off offset:16
	s_waitcnt vmcnt(1)
	v_mov_b32_e32 v158, v150
	s_waitcnt vmcnt(0)
	v_mov_b32_e32 v159, v154
	v_mov_b32_e32 v154, v151
	v_mov_b32_e32 v150, v152
	v_mov_b32_e32 v151, v156
	v_mov_b32_e32 v156, v153
	v_pk_add_f32 v[152:153], v[158:159], v[154:155]
	v_pk_add_f32 v[150:151], v[150:151], v[156:157]
	s_nop 0
	v_pk_add_f32 v[150:151], v[152:153], v[150:151]
	s_nop 0
	v_add_f32_e32 v150, v150, v151
	ds_bpermute_b32 v151, v185, v150
	s_waitcnt lgkmcnt(0)
	v_add_f32_e32 v150, v150, v151
	ds_bpermute_b32 v151, v186, v150
	s_waitcnt lgkmcnt(0)
	v_add_f32_e32 v150, v150, v151
	v_fmamk_f32 v150, v150, 0x3a000000, v184
	v_rsq_f32_e32 v150, v150
	s_nop 0
	v_pk_mul_f32 v[152:153], v[36:37], v[150:151] op_sel_hi:[1,0]
	v_pk_mul_f32 v[154:155], v[38:39], v[150:151] op_sel_hi:[1,0]
	v_pk_mul_f32 v[156:157], v[32:33], v[150:151] op_sel_hi:[1,0]
	v_pk_mul_f32 v[158:159], v[34:35], v[150:151] op_sel_hi:[1,0]
	v_pk_mul_f32 v[160:161], v[4:5], v[150:151] op_sel_hi:[1,0]
	v_pk_mul_f32 v[162:163], v[6:7], v[150:151] op_sel_hi:[1,0]
	v_pk_mul_f32 v[166:167], v[0:1], v[150:151] op_sel_hi:[1,0]
	v_pk_mul_f32 v[150:151], v[2:3], v[150:151] op_sel_hi:[1,0]
	v_pk_mul_f32 v[142:143], v[142:143], v[154:155]
	v_pk_mul_f32 v[140:141], v[140:141], v[152:153]
	v_pk_mul_f32 v[138:139], v[138:139], v[158:159]
	v_pk_mul_f32 v[136:137], v[136:137], v[156:157]
	v_pk_mul_f32 v[134:135], v[134:135], v[162:163]
	v_pk_mul_f32 v[132:133], v[132:133], v[160:161]
	v_pk_mul_f32 v[130:131], v[130:131], v[150:151]
	v_pk_mul_f32 v[128:129], v[128:129], v[166:167]
	global_store_dwordx4 v[164:165], v[140:143], off nt
	global_store_dwordx4 v[164:165], v[136:139], off offset:64 nt
	global_store_dwordx4 v[164:165], v[132:135], off offset:512 nt
	global_store_dwordx4 v[164:165], v[128:131], off offset:576 nt
.Lp2_done:
	s_cbranch_vccnz .LBB0_848
	s_andn2_b64 vcc, exec, s[18:19]
	s_cbranch_vccnz .LBB0_847
	s_barrier
	s_branch .LBB0_847
